# diff-attention prompt item: waves 0-3 run at s_setprio 2 and waves 4-7 at 0 so that the two waves of a SIMD interleave MFMA and softmax VALU phases
# speedup vs baseline: 1.0021x; 1.0021x over previous
.LBB0_1078:
	s_and_b64 vcc, exec, s[0:1]
	s_cbranch_vccz .LBB0_1091
	s_sub_i32 s0, s28, 64
	v_mov_b32_e32 v49, v230
	s_lshr_b32 s33, s0, 5
	s_sub_i32 s1, 31, s33
	v_readfirstlane_b32 s10, v49
	s_lshr_b32 s98, s10, 8
	s_cmp_eq_u32 s98, 0
	s_cbranch_scc1 .Lda_hi
	s_setprio 0
	s_branch .Lda_pr
.Lda_hi:
	s_setprio 2
.Lda_pr:
	s_bfe_u32 s0, s10, 0x10006
	s_ashr_i32 s11, s10, 7
	s_lshl_b32 s10, s28, 8
	s_and_b32 s34, s10, 0x1800
	s_lshl_b32 s10, s1, 6
	s_and_b32 s29, s28, 7
	v_and_b32_e32 v141, 15, v49
	s_or_b32 s10, s34, s10
	v_or_b32_e32 v0, s10, v141
	s_lshl_b32 s10, s29, 8
	s_lshl_b32 s26, s29, 9
	s_add_i32 s29, s29, 1
	v_cvt_f32_ubyte0_e32 v16, s29
	v_ashrrev_i32_e32 v48, 5, v49
	v_exp_f32_e64 v55, -v16
	v_add_u32_e32 v16, s34, v48
	v_ashrrev_i32_e32 v17, 31, v16
	s_lshl_b32 s35, s11, 4
	v_lshlrev_b64 v[16:17], 12, v[16:17]
	v_add_u32_e32 v0, s35, v0
	v_lshl_add_u64 v[16:17], s[22:23], 0, v[16:17]
	v_lshlrev_b32_e32 v18, 4, v49
	v_ashrrev_i32_e32 v1, 31, v0
	v_lshl_add_u64 v[16:17], v[16:17], 0, s[26:27]
	v_and_b32_e32 v50, 0x1f0, v18
	v_mov_b32_e32 v51, v125
	v_lshlrev_b64 v[130:131], 12, v[0:1]
	v_lshl_add_u64 v[40:41], v[16:17], 0, v[50:51]
	s_or_b32 s29, s10, s34
	v_ashrrev_i32_e32 v51, 3, v49
	v_lshl_add_u64 v[0:1], s[20:21], 0, v[130:131]
	v_add_u32_e32 v16, s29, v51
	v_lshl_add_u64 v[0:1], v[0:1], 0, s[26:27]
	s_lshl_b32 s30, s0, 8
	s_mov_b32 s31, s27
	v_ashrrev_i32_e32 v17, 31, v16
	v_lshl_add_u64 v[0:1], v[0:1], 0, s[30:31]
	v_lshlrev_b64 v[132:133], 12, v[16:17]
	s_mov_b32 s31, 0x10000
	v_lshl_add_u64 v[16:17], s[24:25], 0, v[132:133]
	v_and_b32_e32 v52, 0x70, v18
	v_mov_b32_e32 v53, v125
	v_add_co_u32_e32 v24, vcc, s31, v40
	v_lshl_add_u64 v[42:43], v[16:17], 0, v[52:53]
	s_nop 0
	v_addc_co_u32_e32 v25, vcc, 0, v41, vcc
	s_mov_b32 s31, 0x40000
	v_add_co_u32_e32 v28, vcc, s31, v42
	s_mov_b32 s31, 0x20000
	s_nop 0
	v_addc_co_u32_e32 v29, vcc, 0, v43, vcc
	v_add_co_u32_e32 v32, vcc, s31, v40
	s_mov_b32 s31, 0x80000
	s_nop 0
	v_addc_co_u32_e32 v33, vcc, 0, v41, vcc
	v_and_b32_e32 v124, 48, v49
	v_add_co_u32_e32 v36, vcc, s31, v42
	v_lshl_add_u64 v[12:13], v[0:1], 0, v[124:125]
	s_nop 0
	v_addc_co_u32_e32 v37, vcc, 0, v43, vcc
	s_mov_b32 s31, 0x30000
	global_load_dwordx4 v[0:3], v[12:13], off
	global_load_dwordx4 v[4:7], v[12:13], off offset:64
	global_load_dwordx4 v[8:11], v[12:13], off offset:128
	s_nop 0
	global_load_dwordx4 v[12:15], v[12:13], off offset:192
	s_nop 0
	global_load_dwordx4 v[16:19], v[40:41], off
	global_load_dwordx4 v[20:23], v[42:43], off
	v_add_co_u32_e32 v40, vcc, s31, v40
	s_mov_b32 s31, 0xc0000
	s_nop 0
	v_addc_co_u32_e32 v41, vcc, 0, v41, vcc
	v_add_co_u32_e32 v44, vcc, s31, v42
	global_load_dwordx4 v[24:27], v[24:25], off
	s_nop 0
	global_load_dwordx4 v[28:31], v[28:29], off
	v_addc_co_u32_e32 v45, vcc, 0, v43, vcc
	global_load_dwordx4 v[32:35], v[32:33], off
	s_nop 0
	global_load_dwordx4 v[36:39], v[36:37], off
	s_nop 0
	global_load_dwordx4 v[40:43], v[40:41], off
	s_nop 0
	global_load_dwordx4 v[44:47], v[44:45], off
	v_and_b32_e32 v60, 64, v164
	v_and_b32_e32 v54, 63, v49
	v_bfe_u32 v142, v49, 4, 2
	v_xor_b32_e32 v49, 16, v164
	v_add_u32_e32 v60, 64, v60
	v_cmp_lt_i32_e32 vcc, v49, v60
	s_addk_i32 s35, 0x78d
	v_or_b32_e32 v58, 48, v54
	v_cndmask_b32_e32 v49, v164, v49, vcc
	v_lshlrev_b32_e32 v139, 2, v49
	v_xor_b32_e32 v49, 32, v164
	v_cmp_lt_i32_e32 vcc, v49, v60
	v_lshlrev_b32_e32 v138, 2, v142
	s_lshl_b32 s31, s33, 6
	v_cndmask_b32_e32 v49, v164, v49, vcc
	v_lshlrev_b32_e32 v140, 2, v49
	v_or_b32_e32 v49, 0x70, v54
	v_mul_u32_u24_e32 v62, 0x90, v49
	v_or_b32_e32 v49, 0xb0, v54
	v_mul_u32_u24_e32 v63, 0x90, v49
	v_or_b32_e32 v49, 0xf0, v54
	v_mul_u32_u24_e32 v54, 0x90, v49
	v_add_u32_e32 v49, s35, v141
	v_sub_u32_e32 v49, v49, v138
	s_add_i32 s30, s30, 0
	v_lshl_add_u32 v60, v142, 3, 0
	v_subrev_u32_e32 v144, s31, v49
	s_lshl_b32 s31, s28, 20
	v_ashrrev_i32_e32 v49, 31, v48
	v_mul_lo_u32 v53, v48, s7
	v_mul_lo_u32 v51, v51, s52
	v_mov_b32_e32 v56, s30
	v_mul_u32_u24_e32 v143, 0xa0, v141
	v_lshl_add_u32 v143, v142, 4, v143
	v_add_u32_e32 v143, 0x8400, v143
	s_and_b32 s34, s31, 0x1800000
	s_mov_b32 s35, s27
	v_lshlrev_b64 v[48:49], 12, v[48:49]
	v_mul_f32_e32 v135, 0x3fb8aa3b, v55
	v_add_u32_e32 v53, 0, v53
	v_add_u32_e32 v51, 0, v51
	v_mul_u32_u24_e32 v55, 0x210, v141
	v_mad_u32_u24 v56, v141, s7, v56
	v_add_u32_e32 v57, s30, v124
	v_mul_u32_u24_e32 v59, 0x210, v58
	v_add_u32_e32 v61, 0x8400, v143
	v_mul_u32_u24_e32 v58, 0x90, v58
	v_add_u32_e32 v64, 0x8440, v143
	v_lshl_add_u64 v[136:137], s[34:35], 0, v[48:49]
	v_mov_b32_e32 v155, 0
	s_mov_b32 s29, 0
	s_sub_i32 s30, 32, s33
	v_or_b32_e32 v132, v132, v52
	v_or3_b32 v136, v136, s26, v50
	v_mov_b32_e32 v156, 0xff800000
	v_add_u32_e32 v145, v53, v50
	v_lshrrev_b32_e32 v146, 3, v230
	v_mul_u32_u24_e32 v146, 0xa0, v146
	v_and_b32_e32 v203, 4, v230
	v_lshl_add_u32 v146, v203, 4, v146
	v_and_b32_e32 v203, 1, v230
	v_lshl_add_u32 v146, v203, 5, v146
	v_and_b32_e32 v203, 2, v230
	v_lshl_add_u32 v146, v203, 2, v146
	v_add_u32_e32 v124, v56, v124
	v_add_u32_e32 v147, v57, v55
	v_add_u32_e32 v148, v57, v59
	v_add_u32_e32 v149, v60, v58
	v_add_u32_e32 v150, v60, v62
	v_add_u32_e32 v151, v60, v63
	v_add_u32_e32 v152, v60, v54
	v_add_u32_e32 v153, 0x7800, v61
	v_add_u32_e32 v154, 0x7800, v64
	v_mov_b32_e32 v48, 0
	v_mov_b32_e32 v49, v155
	v_mov_b32_e32 v50, v155
	v_mov_b32_e32 v51, v155
	v_mov_b32_e32 v52, 0
	v_mov_b32_e32 v53, v155
	v_mov_b32_e32 v54, v155
	v_mov_b32_e32 v55, v155
	v_mov_b32_e32 v56, 0
	v_mov_b32_e32 v57, v155
	v_mov_b32_e32 v58, v155
	v_mov_b32_e32 v59, v155
	v_mov_b32_e32 v60, 0
	v_mov_b32_e32 v61, v155
	v_mov_b32_e32 v62, v155
	v_mov_b32_e32 v63, v155
	v_mov_b32_e32 v64, 0
	v_mov_b32_e32 v65, v155
	v_mov_b32_e32 v66, v155
	v_mov_b32_e32 v67, v155
	v_mov_b32_e32 v68, 0
	v_mov_b32_e32 v69, v155
	v_mov_b32_e32 v70, v155
	v_mov_b32_e32 v71, v155
	v_mov_b32_e32 v72, 0
	v_mov_b32_e32 v73, v155
	v_mov_b32_e32 v74, v155
	v_mov_b32_e32 v75, v155
	v_mov_b32_e32 v76, 0
	v_mov_b32_e32 v77, v155
	v_mov_b32_e32 v78, v155
	v_mov_b32_e32 v79, v155
	v_mov_b32_e32 v80, 0
	v_mov_b32_e32 v81, v155
	v_mov_b32_e32 v82, v155
	v_mov_b32_e32 v83, v155
	v_mov_b32_e32 v84, 0
	v_mov_b32_e32 v85, v155
	v_mov_b32_e32 v86, v155
	v_mov_b32_e32 v87, v155
	v_mov_b32_e32 v88, 0
	v_mov_b32_e32 v89, v155
	v_mov_b32_e32 v90, v155
	v_mov_b32_e32 v91, v155
	v_mov_b32_e32 v96, 0
	v_mov_b32_e32 v97, v155
	v_mov_b32_e32 v98, v155
	v_mov_b32_e32 v99, v155
	v_mov_b32_e32 v92, 0
	v_mov_b32_e32 v93, v155
	v_mov_b32_e32 v94, v155
	v_mov_b32_e32 v95, v155
	v_mov_b32_e32 v100, 0
	v_mov_b32_e32 v101, v155
	v_mov_b32_e32 v102, v155
	v_mov_b32_e32 v103, v155
	v_mov_b32_e32 v104, 0
	v_mov_b32_e32 v105, v155
	v_mov_b32_e32 v106, v155
	v_mov_b32_e32 v107, v155
	v_mov_b32_e32 v108, 0
	v_mov_b32_e32 v109, v155
	v_mov_b32_e32 v110, v155
	v_mov_b32_e32 v111, v155
	v_add_u32_e32 v204, 51, v144
	v_cvt_f32_i32_e32 v204, v204
	v_add_u32_e32 v205, 50, v144
	v_cvt_f32_i32_e32 v205, v205
	v_add_u32_e32 v206, 49, v144
	v_cvt_f32_i32_e32 v206, v206
	v_add_u32_e32 v207, 48, v144
	v_cvt_f32_i32_e32 v207, v207
	v_add_u32_e32 v208, 35, v144
	v_cvt_f32_i32_e32 v208, v208
	v_add_u32_e32 v209, 34, v144
	v_cvt_f32_i32_e32 v209, v209
	v_add_u32_e32 v210, 33, v144
	v_cvt_f32_i32_e32 v210, v210
	v_add_u32_e32 v211, 32, v144
	v_cvt_f32_i32_e32 v211, v211
	v_add_u32_e32 v212, 19, v144
	v_cvt_f32_i32_e32 v212, v212
	v_add_u32_e32 v213, 18, v144
	v_cvt_f32_i32_e32 v213, v213
	v_add_u32_e32 v214, 17, v144
	v_cvt_f32_i32_e32 v214, v214
	v_add_u32_e32 v215, 16, v144
	v_cvt_f32_i32_e32 v215, v215
	v_add_u32_e32 v216, 3, v144
	v_cvt_f32_i32_e32 v216, v216
	v_add_u32_e32 v217, 2, v144
	v_cvt_f32_i32_e32 v217, v217
	v_add_u32_e32 v218, 1, v144
	v_cvt_f32_i32_e32 v218, v218
	v_add_u32_e32 v219, 0, v144
	v_cvt_f32_i32_e32 v219, v219
	v_mul_f32_e32 v204, v135, v204
	v_mul_f32_e32 v205, v135, v205
	v_mul_f32_e32 v206, v135, v206
	v_mul_f32_e32 v207, v135, v207
	v_mul_f32_e32 v208, v135, v208
	v_mul_f32_e32 v209, v135, v209
	v_mul_f32_e32 v210, v135, v210
	v_mul_f32_e32 v211, v135, v211
	v_mul_f32_e32 v212, v135, v212
	v_mul_f32_e32 v213, v135, v213
	v_mul_f32_e32 v214, v135, v214
	v_mul_f32_e32 v215, v135, v215
	v_mul_f32_e32 v216, v135, v216
	v_mul_f32_e32 v217, v135, v217
	v_mul_f32_e32 v218, v135, v218
	v_mul_f32_e32 v219, v135, v219
	v_mul_f32_e32 v220, 0x42800000, v135
	v_cvt_f32_u32_e32 v221, s1
	v_mul_f32_e32 v221, v221, v220

.LBB0_1090:
	s_setprio 0
	s_barrier
